# grid barrier: waiters poll the TOP arrival counter against (gen+1)*nx instead of the TOPGEN flag; the last XCD leader no longer publishes TOPGEN (one atomic round trip less before release)
# baseline (speedup 1.0000x reference)
.LBB0_367:
	v_readlane_b32 s4, v253, 11
	v_readlane_b32 s5, v253, 12
	v_mov_b32_e32 v1, 1
	v_sub_u32_e32 v4, 0, v2
	s_nop 2
	global_atomic_add v3, v145, v1, s[4:5] sc0
	v_cvt_f32_u32_e32 v1, v2
	v_rcp_iflag_f32_e32 v1, v1
	s_nop 0
	v_mul_f32_e32 v1, 0x4f7ffffe, v1
	v_cvt_u32_f32_e32 v1, v1
	v_mul_lo_u32 v4, v4, v1
	v_mul_hi_u32 v4, v1, v4
	v_add_u32_e32 v1, v1, v4
	s_waitcnt vmcnt(0)
	v_mul_hi_u32 v1, v3, v1
	v_mul_lo_u32 v4, v1, v2
	v_sub_u32_e32 v4, v3, v4
	v_add_u32_e32 v5, 1, v1
	v_cmp_ge_u32_e32 vcc, v4, v2
	v_add_u32_e32 v3, 1, v3
	s_nop 0
	v_cndmask_b32_e32 v1, v1, v5, vcc
	v_sub_u32_e32 v5, v4, v2
	v_cndmask_b32_e32 v4, v4, v5, vcc
	v_add_u32_e32 v5, 1, v1
	v_cmp_ge_u32_e32 vcc, v4, v2
	s_nop 1
	v_cndmask_b32_e32 v1, v1, v5, vcc
	v_mul_lo_u32 v4, v2, v1
	v_add_u32_e32 v2, v4, v2
	v_cmp_ne_u32_e32 vcc, v3, v2
	s_and_saveexec_b64 s[4:5], vcc
	s_xor_b64 s[4:5], exec, s[4:5]
	s_cbranch_execz .LBB0_381
	v_readlane_b32 s6, v253, 15
	v_readlane_b32 s7, v253, 16
	s_waitcnt lgkmcnt(0)
	v_add_u32_e32 v1, 1, v1
	v_mul_lo_u32 v1, v1, v0
	s_nop 3
	global_load_dword v0, v145, s[6:7] sc1
	s_waitcnt vmcnt(0)
	v_cmp_lt_u32_e32 vcc, v0, v1
	s_and_saveexec_b64 s[6:7], vcc
	s_cbranch_execz .LBB0_380
	s_mov_b32 s17, 1
	s_mov_b64 s[44:45], 0
	s_branch .LBB0_371

.LBB0_373:
	v_readlane_b32 s18, v253, 15
	v_readlane_b32 s19, v253, 16
	s_add_i32 s17, s17, 1
	s_mov_b64 s[68:69], -1
	s_nop 2
	global_load_dword v0, v145, s[18:19] sc1
	s_waitcnt vmcnt(0)
	v_cmp_ge_u32_e32 vcc, v0, v1
	s_orn2_b64 s[52:53], vcc, exec
	s_branch .LBB0_370

.LBB0_384:
	s_or_b64 exec, exec, s[6:7]
	s_waitcnt vmcnt(0)
	v_readfirstlane_b32 s4, v2
	v_cvt_f32_u32_e32 v2, v0
	v_sub_u32_e32 v3, 0, v0
	v_add_u32_e32 v1, s4, v1
	v_readlane_b32 s4, v253, 17
	v_rcp_iflag_f32_e32 v2, v2
	v_readlane_b32 s5, v253, 18
	s_mov_b64 s[6:7], 0
	v_mul_f32_e32 v2, 0x4f7ffffe, v2
	v_cvt_u32_f32_e32 v2, v2
	v_mul_lo_u32 v3, v3, v2
	v_mul_hi_u32 v3, v2, v3
	v_add_u32_e32 v2, v2, v3
	v_mul_hi_u32 v2, v1, v2
	v_mul_lo_u32 v3, v2, v0
	v_sub_u32_e32 v3, v1, v3
	v_cmp_ge_u32_e32 vcc, v3, v0
	v_add_u32_e32 v4, 1, v2
	v_add_u32_e32 v1, 1, v1
	v_cndmask_b32_e32 v2, v2, v4, vcc
	v_sub_u32_e32 v4, v3, v0
	v_cndmask_b32_e32 v3, v3, v4, vcc
	v_cmp_ge_u32_e32 vcc, v3, v0
	v_add_u32_e32 v3, 1, v2
	s_nop 0
	v_cndmask_b32_e32 v2, v2, v3, vcc
	v_mul_lo_u32 v3, v0, v2
	v_add_u32_e32 v0, v3, v0
	v_cmp_ne_u32_e32 vcc, v1, v0
	v_mov_b32_e32 v2, v0
	v_mov_b64_e32 v[0:1], s[4:5]
	s_and_saveexec_b64 s[4:5], vcc
	s_cbranch_execz .LBB0_396
	v_readlane_b32 s6, v253, 15
	v_readlane_b32 s7, v253, 16
	s_mov_b64 s[44:45], 0
	s_nop 3
	global_load_dword v0, v145, s[6:7] sc1
	s_waitcnt vmcnt(0)
	v_cmp_lt_u32_e32 vcc, v0, v2
	s_and_saveexec_b64 s[6:7], vcc
	s_cbranch_execz .LBB0_395
	s_mov_b32 s17, 1
	s_branch .LBB0_388

.LBB0_390:
	v_readlane_b32 s18, v253, 15
	v_readlane_b32 s19, v253, 16
	s_add_i32 s17, s17, 1
	s_mov_b64 s[68:69], -1
	s_nop 2
	global_load_dword v0, v145, s[18:19] sc1
	s_waitcnt vmcnt(0)
	v_cmp_ge_u32_e32 vcc, v0, v2
	s_orn2_b64 s[52:53], vcc, exec
	s_branch .LBB0_387

.LBB0_1011:
	v_readlane_b32 s4, v253, 11
	v_readlane_b32 s5, v253, 12
	v_mov_b32_e32 v1, 1
	v_sub_u32_e32 v4, 0, v2
	s_nop 2
	global_atomic_add v3, v145, v1, s[4:5] sc0
	v_cvt_f32_u32_e32 v1, v2
	v_rcp_iflag_f32_e32 v1, v1
	s_nop 0
	v_mul_f32_e32 v1, 0x4f7ffffe, v1
	v_cvt_u32_f32_e32 v1, v1
	v_mul_lo_u32 v4, v4, v1
	v_mul_hi_u32 v4, v1, v4
	v_add_u32_e32 v1, v1, v4
	s_waitcnt vmcnt(0)
	v_mul_hi_u32 v1, v3, v1
	v_mul_lo_u32 v4, v1, v2
	v_sub_u32_e32 v4, v3, v4
	v_add_u32_e32 v5, 1, v1
	v_cmp_ge_u32_e32 vcc, v4, v2
	v_add_u32_e32 v3, 1, v3
	s_nop 0
	v_cndmask_b32_e32 v1, v1, v5, vcc
	v_sub_u32_e32 v5, v4, v2
	v_cndmask_b32_e32 v4, v4, v5, vcc
	v_add_u32_e32 v5, 1, v1
	v_cmp_ge_u32_e32 vcc, v4, v2
	s_nop 1
	v_cndmask_b32_e32 v1, v1, v5, vcc
	v_mul_lo_u32 v4, v2, v1
	v_add_u32_e32 v2, v4, v2
	v_cmp_ne_u32_e32 vcc, v3, v2
	s_and_saveexec_b64 s[4:5], vcc
	s_xor_b64 s[4:5], exec, s[4:5]
	s_cbranch_execz .LBB0_1025
	v_readlane_b32 s6, v253, 15
	v_readlane_b32 s7, v253, 16
	s_waitcnt lgkmcnt(0)
	v_add_u32_e32 v1, 1, v1
	v_mul_lo_u32 v1, v1, v0
	s_nop 3
	global_load_dword v0, v145, s[6:7] sc1
	s_waitcnt vmcnt(0)
	v_cmp_lt_u32_e32 vcc, v0, v1
	s_and_saveexec_b64 s[6:7], vcc
	s_cbranch_execz .LBB0_1024
	s_mov_b32 s17, 1
	s_mov_b64 s[42:43], 0
	s_branch .LBB0_1015

.LBB0_1028:
	s_or_b64 exec, exec, s[6:7]
	s_waitcnt vmcnt(0)
	v_readfirstlane_b32 s4, v2
	v_cvt_f32_u32_e32 v2, v0
	v_sub_u32_e32 v3, 0, v0
	v_add_u32_e32 v1, s4, v1
	v_readlane_b32 s4, v253, 17
	v_rcp_iflag_f32_e32 v2, v2
	v_readlane_b32 s5, v253, 18
	s_mov_b64 s[6:7], 0
	v_mul_f32_e32 v2, 0x4f7ffffe, v2
	v_cvt_u32_f32_e32 v2, v2
	v_mul_lo_u32 v3, v3, v2
	v_mul_hi_u32 v3, v2, v3
	v_add_u32_e32 v2, v2, v3
	v_mul_hi_u32 v2, v1, v2
	v_mul_lo_u32 v3, v2, v0
	v_sub_u32_e32 v3, v1, v3
	v_cmp_ge_u32_e32 vcc, v3, v0
	v_add_u32_e32 v4, 1, v2
	v_add_u32_e32 v1, 1, v1
	v_cndmask_b32_e32 v2, v2, v4, vcc
	v_sub_u32_e32 v4, v3, v0
	v_cndmask_b32_e32 v3, v3, v4, vcc
	v_cmp_ge_u32_e32 vcc, v3, v0
	v_add_u32_e32 v3, 1, v2
	s_nop 0
	v_cndmask_b32_e32 v2, v2, v3, vcc
	v_mul_lo_u32 v3, v0, v2
	v_add_u32_e32 v0, v3, v0
	v_cmp_ne_u32_e32 vcc, v1, v0
	v_mov_b32_e32 v2, v0
	v_mov_b64_e32 v[0:1], s[4:5]
	s_and_saveexec_b64 s[4:5], vcc
	s_cbranch_execz .LBB0_1040
	v_readlane_b32 s6, v253, 15
	v_readlane_b32 s7, v253, 16
	s_mov_b64 s[42:43], 0
	s_nop 3
	global_load_dword v0, v145, s[6:7] sc1
	s_waitcnt vmcnt(0)
	v_cmp_lt_u32_e32 vcc, v0, v2
	s_and_saveexec_b64 s[6:7], vcc
	s_cbranch_execz .LBB0_1039
	s_mov_b32 s17, 1
	s_branch .LBB0_1032

.LBB0_1071:
	v_readlane_b32 s4, v253, 11
	v_readlane_b32 s5, v253, 12
	v_mov_b32_e32 v1, 1
	v_sub_u32_e32 v4, 0, v2
	s_nop 2
	global_atomic_add v3, v145, v1, s[4:5] sc0
	v_cvt_f32_u32_e32 v1, v2
	v_rcp_iflag_f32_e32 v1, v1
	s_nop 0
	v_mul_f32_e32 v1, 0x4f7ffffe, v1
	v_cvt_u32_f32_e32 v1, v1
	v_mul_lo_u32 v4, v4, v1
	v_mul_hi_u32 v4, v1, v4
	v_add_u32_e32 v1, v1, v4
	s_waitcnt vmcnt(0)
	v_mul_hi_u32 v1, v3, v1
	v_mul_lo_u32 v4, v1, v2
	v_sub_u32_e32 v4, v3, v4
	v_add_u32_e32 v5, 1, v1
	v_cmp_ge_u32_e32 vcc, v4, v2
	v_add_u32_e32 v3, 1, v3
	s_nop 0
	v_cndmask_b32_e32 v1, v1, v5, vcc
	v_sub_u32_e32 v5, v4, v2
	v_cndmask_b32_e32 v4, v4, v5, vcc
	v_add_u32_e32 v5, 1, v1
	v_cmp_ge_u32_e32 vcc, v4, v2
	s_nop 1
	v_cndmask_b32_e32 v1, v1, v5, vcc
	v_mul_lo_u32 v4, v2, v1
	v_add_u32_e32 v2, v4, v2
	v_cmp_ne_u32_e32 vcc, v3, v2
	s_and_saveexec_b64 s[4:5], vcc
	s_xor_b64 s[4:5], exec, s[4:5]
	s_cbranch_execz .LBB0_1085
	v_readlane_b32 s6, v253, 15
	v_readlane_b32 s7, v253, 16
	s_waitcnt lgkmcnt(0)
	v_add_u32_e32 v1, 1, v1
	v_mul_lo_u32 v1, v1, v0
	s_nop 3
	global_load_dword v0, v145, s[6:7] sc1
	s_waitcnt vmcnt(0)
	v_cmp_lt_u32_e32 vcc, v0, v1
	s_and_saveexec_b64 s[6:7], vcc
	s_cbranch_execz .LBB0_1084
	s_mov_b32 s16, 1
	s_mov_b64 s[42:43], 0
	s_branch .LBB0_1075

.LBB0_1077:
	v_readlane_b32 s18, v253, 15
	v_readlane_b32 s19, v253, 16
	s_add_i32 s16, s16, 1
	s_mov_b64 s[52:53], -1
	s_nop 2
	global_load_dword v0, v145, s[18:19] sc1
	s_waitcnt vmcnt(0)
	v_cmp_ge_u32_e32 vcc, v0, v1
	s_orn2_b64 s[46:47], vcc, exec
	s_branch .LBB0_1074

.LBB0_1088:
	s_or_b64 exec, exec, s[6:7]
	s_waitcnt vmcnt(0)
	v_readfirstlane_b32 s4, v2
	v_cvt_f32_u32_e32 v2, v0
	v_sub_u32_e32 v3, 0, v0
	v_add_u32_e32 v1, s4, v1
	v_readlane_b32 s4, v253, 17
	v_rcp_iflag_f32_e32 v2, v2
	v_readlane_b32 s5, v253, 18
	s_mov_b64 s[6:7], 0
	v_mul_f32_e32 v2, 0x4f7ffffe, v2
	v_cvt_u32_f32_e32 v2, v2
	v_mul_lo_u32 v3, v3, v2
	v_mul_hi_u32 v3, v2, v3
	v_add_u32_e32 v2, v2, v3
	v_mul_hi_u32 v2, v1, v2
	v_mul_lo_u32 v3, v2, v0
	v_sub_u32_e32 v3, v1, v3
	v_cmp_ge_u32_e32 vcc, v3, v0
	v_add_u32_e32 v4, 1, v2
	v_add_u32_e32 v1, 1, v1
	v_cndmask_b32_e32 v2, v2, v4, vcc
	v_sub_u32_e32 v4, v3, v0
	v_cndmask_b32_e32 v3, v3, v4, vcc
	v_cmp_ge_u32_e32 vcc, v3, v0
	v_add_u32_e32 v3, 1, v2
	s_nop 0
	v_cndmask_b32_e32 v2, v2, v3, vcc
	v_mul_lo_u32 v3, v0, v2
	v_add_u32_e32 v0, v3, v0
	v_cmp_ne_u32_e32 vcc, v1, v0
	v_mov_b32_e32 v2, v0
	v_mov_b64_e32 v[0:1], s[4:5]
	s_and_saveexec_b64 s[4:5], vcc
	s_cbranch_execz .LBB0_1100
	v_readlane_b32 s6, v253, 15
	v_readlane_b32 s7, v253, 16
	s_mov_b64 s[42:43], 0
	s_nop 3
	global_load_dword v0, v145, s[6:7] sc1
	s_waitcnt vmcnt(0)
	v_cmp_lt_u32_e32 vcc, v0, v2
	s_and_saveexec_b64 s[6:7], vcc
	s_cbranch_execz .LBB0_1099
	s_mov_b32 s16, 1
	s_branch .LBB0_1092

.LBB0_1094:
	v_readlane_b32 s18, v253, 15
	v_readlane_b32 s19, v253, 16
	s_add_i32 s16, s16, 1
	s_mov_b64 s[52:53], -1
	s_nop 2
	global_load_dword v0, v145, s[18:19] sc1
	s_waitcnt vmcnt(0)
	v_cmp_ge_u32_e32 vcc, v0, v2
	s_orn2_b64 s[46:47], vcc, exec
	s_branch .LBB0_1091

.LBB0_1242:
	v_readlane_b32 s6, v253, 11
	v_mov_b32_e32 v3, 0
	v_mov_b32_e32 v1, 1
	v_readlane_b32 s7, v253, 12
	v_sub_u32_e32 v5, 0, v2
	s_nop 3
	global_atomic_add v4, v3, v1, s[6:7] sc0
	v_cvt_f32_u32_e32 v1, v2
	v_rcp_iflag_f32_e32 v1, v1
	s_nop 0
	v_mul_f32_e32 v1, 0x4f7ffffe, v1
	v_cvt_u32_f32_e32 v1, v1
	v_mul_lo_u32 v5, v5, v1
	v_mul_hi_u32 v5, v1, v5
	v_add_u32_e32 v1, v1, v5
	s_waitcnt vmcnt(0)
	v_mul_hi_u32 v1, v4, v1
	v_mul_lo_u32 v5, v1, v2
	v_sub_u32_e32 v5, v4, v5
	v_add_u32_e32 v6, 1, v1
	v_cmp_ge_u32_e32 vcc, v5, v2
	v_add_u32_e32 v4, 1, v4
	s_nop 0
	v_cndmask_b32_e32 v1, v1, v6, vcc
	v_sub_u32_e32 v6, v5, v2
	v_cndmask_b32_e32 v5, v5, v6, vcc
	v_add_u32_e32 v6, 1, v1
	v_cmp_ge_u32_e32 vcc, v5, v2
	s_nop 1
	v_cndmask_b32_e32 v1, v1, v6, vcc
	v_mul_lo_u32 v5, v2, v1
	v_add_u32_e32 v2, v5, v2
	v_cmp_ne_u32_e32 vcc, v4, v2
	s_and_saveexec_b64 s[6:7], vcc
	s_xor_b64 s[6:7], exec, s[6:7]
	s_cbranch_execz .LBB0_1256
	v_readlane_b32 s8, v253, 15
	v_readlane_b32 s9, v253, 16
	s_waitcnt lgkmcnt(0)
	v_add_u32_e32 v1, 1, v1
	v_mul_lo_u32 v1, v1, v0
	s_nop 3
	global_load_dword v0, v3, s[8:9] sc1
	s_waitcnt vmcnt(0)
	v_cmp_lt_u32_e32 vcc, v0, v1
	s_and_saveexec_b64 s[8:9], vcc
	s_cbranch_execz .LBB0_1255
	s_mov_b32 s20, 1
	s_mov_b64 s[10:11], 0
	v_mov_b32_e32 v0, 0
	s_branch .LBB0_1246

.LBB0_1248:
	v_readlane_b32 s14, v253, 15
	v_readlane_b32 s15, v253, 16
	s_add_i32 s20, s20, 1
	s_mov_b64 s[16:17], -1
	s_nop 2
	global_load_dword v2, v0, s[14:15] sc1
	s_waitcnt vmcnt(0)
	v_cmp_ge_u32_e32 vcc, v2, v1
	s_orn2_b64 s[14:15], vcc, exec
	s_branch .LBB0_1245

.LBB0_1259:
	s_or_b64 exec, exec, s[8:9]
	v_cvt_f32_u32_e32 v3, v0
	s_waitcnt vmcnt(0)
	v_readfirstlane_b32 s6, v2
	s_mov_b64 s[8:9], 0
	v_rcp_iflag_f32_e32 v3, v3
	v_add_u32_e32 v1, s6, v1
	v_add_u32_e32 v4, 1, v1
	v_readlane_b32 s6, v253, 17
	v_mul_f32_e32 v2, 0x4f7ffffe, v3
	v_cvt_u32_f32_e32 v2, v2
	v_sub_u32_e32 v3, 0, v0
	v_readlane_b32 s7, v253, 18
	v_mul_lo_u32 v3, v3, v2
	v_mul_hi_u32 v3, v2, v3
	v_add_u32_e32 v2, v2, v3
	v_mul_hi_u32 v2, v1, v2
	v_mul_lo_u32 v3, v2, v0
	v_sub_u32_e32 v1, v1, v3
	v_add_u32_e32 v5, 1, v2
	v_cmp_ge_u32_e32 vcc, v1, v0
	v_sub_u32_e32 v3, v1, v0
	s_nop 0
	v_cndmask_b32_e32 v2, v2, v5, vcc
	v_cndmask_b32_e32 v1, v1, v3, vcc
	v_add_u32_e32 v3, 1, v2
	v_cmp_ge_u32_e32 vcc, v1, v0
	s_nop 1
	v_cndmask_b32_e32 v2, v2, v3, vcc
	v_mul_lo_u32 v1, v0, v2
	v_add_u32_e32 v0, v1, v0
	v_cmp_ne_u32_e32 vcc, v4, v0
	v_mov_b32_e32 v2, v0
	v_mov_b64_e32 v[0:1], s[6:7]
	s_and_saveexec_b64 s[6:7], vcc
	s_cbranch_execz .LBB0_1271
	v_readlane_b32 s8, v253, 15
	v_mov_b32_e32 v0, 0
	v_readlane_b32 s9, v253, 16
	s_mov_b64 s[10:11], 0
	s_nop 3
	global_load_dword v1, v0, s[8:9] sc1
	s_waitcnt vmcnt(0)
	v_cmp_lt_u32_e32 vcc, v1, v2
	s_and_saveexec_b64 s[8:9], vcc
	s_cbranch_execz .LBB0_1270
	s_mov_b32 s20, 1
	s_branch .LBB0_1263

.LBB0_1265:
	v_readlane_b32 s14, v253, 15
	v_readlane_b32 s15, v253, 16
	s_add_i32 s20, s20, 1
	s_nop 3
	global_load_dword v1, v0, s[14:15] sc1
	s_mov_b64 s[14:15], -1
	s_waitcnt vmcnt(0)
	v_cmp_ge_u32_e32 vcc, v1, v2
	s_orn2_b64 s[18:19], vcc, exec
	s_branch .LBB0_1262

.LBB0_1308:
	v_readlane_b32 s4, v253, 11
	v_mov_b32_e32 v3, 0
	v_mov_b32_e32 v1, 1
	v_readlane_b32 s5, v253, 12
	v_sub_u32_e32 v5, 0, v2
	s_nop 3
	global_atomic_add v4, v3, v1, s[4:5] sc0
	v_cvt_f32_u32_e32 v1, v2
	v_rcp_iflag_f32_e32 v1, v1
	s_nop 0
	v_mul_f32_e32 v1, 0x4f7ffffe, v1
	v_cvt_u32_f32_e32 v1, v1
	v_mul_lo_u32 v5, v5, v1
	v_mul_hi_u32 v5, v1, v5
	v_add_u32_e32 v1, v1, v5
	s_waitcnt vmcnt(0)
	v_mul_hi_u32 v1, v4, v1
	v_mul_lo_u32 v5, v1, v2
	v_sub_u32_e32 v5, v4, v5
	v_add_u32_e32 v6, 1, v1
	v_cmp_ge_u32_e32 vcc, v5, v2
	v_add_u32_e32 v4, 1, v4
	s_nop 0
	v_cndmask_b32_e32 v1, v1, v6, vcc
	v_sub_u32_e32 v6, v5, v2
	v_cndmask_b32_e32 v5, v5, v6, vcc
	v_add_u32_e32 v6, 1, v1
	v_cmp_ge_u32_e32 vcc, v5, v2
	s_nop 1
	v_cndmask_b32_e32 v1, v1, v6, vcc
	v_mul_lo_u32 v5, v2, v1
	v_add_u32_e32 v2, v5, v2
	v_cmp_ne_u32_e32 vcc, v4, v2
	s_and_saveexec_b64 s[4:5], vcc
	s_xor_b64 s[4:5], exec, s[4:5]
	s_cbranch_execz .LBB0_1322
	v_readlane_b32 s6, v253, 15
	v_readlane_b32 s7, v253, 16
	s_waitcnt lgkmcnt(0)
	v_add_u32_e32 v1, 1, v1
	v_mul_lo_u32 v1, v1, v0
	s_nop 3
	global_load_dword v0, v3, s[6:7] sc1
	s_waitcnt vmcnt(0)
	v_cmp_lt_u32_e32 vcc, v0, v1
	s_and_saveexec_b64 s[6:7], vcc
	s_cbranch_execz .LBB0_1321
	s_mov_b32 s18, 1
	s_mov_b64 s[8:9], 0
	v_mov_b32_e32 v0, 0
	s_branch .LBB0_1312

.LBB0_1314:
	v_readlane_b32 s12, v253, 15
	v_readlane_b32 s13, v253, 16
	s_add_i32 s18, s18, 1
	s_mov_b64 s[14:15], -1
	s_nop 2
	global_load_dword v2, v0, s[12:13] sc1
	s_waitcnt vmcnt(0)
	v_cmp_ge_u32_e32 vcc, v2, v1
	s_orn2_b64 s[12:13], vcc, exec
	s_branch .LBB0_1311

.LBB0_1325:
	s_or_b64 exec, exec, s[6:7]
	v_cvt_f32_u32_e32 v3, v0
	s_waitcnt vmcnt(0)
	v_readfirstlane_b32 s4, v2
	s_mov_b64 s[6:7], 0
	v_rcp_iflag_f32_e32 v3, v3
	v_add_u32_e32 v1, s4, v1
	v_add_u32_e32 v4, 1, v1
	v_readlane_b32 s4, v253, 17
	v_mul_f32_e32 v2, 0x4f7ffffe, v3
	v_cvt_u32_f32_e32 v2, v2
	v_sub_u32_e32 v3, 0, v0
	v_readlane_b32 s5, v253, 18
	v_mul_lo_u32 v3, v3, v2
	v_mul_hi_u32 v3, v2, v3
	v_add_u32_e32 v2, v2, v3
	v_mul_hi_u32 v2, v1, v2
	v_mul_lo_u32 v3, v2, v0
	v_sub_u32_e32 v1, v1, v3
	v_add_u32_e32 v5, 1, v2
	v_cmp_ge_u32_e32 vcc, v1, v0
	v_sub_u32_e32 v3, v1, v0
	s_nop 0
	v_cndmask_b32_e32 v2, v2, v5, vcc
	v_cndmask_b32_e32 v1, v1, v3, vcc
	v_add_u32_e32 v3, 1, v2
	v_cmp_ge_u32_e32 vcc, v1, v0
	s_nop 1
	v_cndmask_b32_e32 v2, v2, v3, vcc
	v_mul_lo_u32 v1, v0, v2
	v_add_u32_e32 v0, v1, v0
	v_cmp_ne_u32_e32 vcc, v4, v0
	v_mov_b32_e32 v2, v0
	v_mov_b64_e32 v[0:1], s[4:5]
	s_and_saveexec_b64 s[4:5], vcc
	s_cbranch_execz .LBB0_1337
	v_readlane_b32 s6, v253, 15
	v_mov_b32_e32 v0, 0
	v_readlane_b32 s7, v253, 16
	s_mov_b64 s[8:9], 0
	s_nop 3
	global_load_dword v1, v0, s[6:7] sc1
	s_waitcnt vmcnt(0)
	v_cmp_lt_u32_e32 vcc, v1, v2
	s_and_saveexec_b64 s[6:7], vcc
	s_cbranch_execz .LBB0_1336
	s_mov_b32 s18, 1
	s_branch .LBB0_1329

.LBB0_1331:
	v_readlane_b32 s12, v253, 15
	v_readlane_b32 s13, v253, 16
	s_add_i32 s18, s18, 1
	s_nop 3
	global_load_dword v1, v0, s[12:13] sc1
	s_mov_b64 s[12:13], -1
	s_waitcnt vmcnt(0)
	v_cmp_ge_u32_e32 vcc, v1, v2
	s_orn2_b64 s[16:17], vcc, exec
	s_branch .LBB0_1328

.LBB0_1550:
	v_readlane_b32 s4, v253, 11
	v_readlane_b32 s5, v253, 12
	v_cvt_f32_u32_e32 v0, v3
	v_sub_u32_e32 v5, 0, v3
	v_rcp_iflag_f32_e32 v0, v0
	s_nop 1
	global_atomic_add v4, v1, v252, s[4:5] sc0
	v_mul_f32_e32 v0, 0x4f7ffffe, v0
	v_cvt_u32_f32_e32 v0, v0
	v_mul_lo_u32 v5, v5, v0
	v_mul_hi_u32 v5, v0, v5
	v_add_u32_e32 v0, v0, v5
	s_waitcnt vmcnt(0)
	v_mul_hi_u32 v0, v4, v0
	v_mul_lo_u32 v5, v0, v3
	v_sub_u32_e32 v5, v4, v5
	v_add_u32_e32 v6, 1, v0
	v_cmp_ge_u32_e32 vcc, v5, v3
	v_add_u32_e32 v4, 1, v4
	s_nop 0
	v_cndmask_b32_e32 v0, v0, v6, vcc
	v_sub_u32_e32 v6, v5, v3
	v_cndmask_b32_e32 v5, v5, v6, vcc
	v_add_u32_e32 v6, 1, v0
	v_cmp_ge_u32_e32 vcc, v5, v3
	s_nop 1
	v_cndmask_b32_e32 v0, v0, v6, vcc
	v_mul_lo_u32 v5, v3, v0
	v_add_u32_e32 v3, v5, v3
	v_cmp_ne_u32_e32 vcc, v4, v3
	s_and_saveexec_b64 s[4:5], vcc
	s_xor_b64 s[4:5], exec, s[4:5]
	s_cbranch_execz .LBB0_1564
	v_readlane_b32 s6, v253, 15
	v_readlane_b32 s7, v253, 16
	s_waitcnt lgkmcnt(0)
	v_add_u32_e32 v0, 1, v0
	v_mul_lo_u32 v0, v0, v2
	s_nop 3
	global_load_dword v2, v1, s[6:7] sc1
	s_waitcnt vmcnt(0)
	v_cmp_lt_u32_e32 vcc, v2, v0
	s_and_saveexec_b64 s[6:7], vcc
	s_cbranch_execz .LBB0_1563
	s_mov_b32 s18, 1
	s_mov_b64 s[8:9], 0
	s_branch .LBB0_1554

.LBB0_1556:
	v_readlane_b32 s12, v253, 15
	v_readlane_b32 s13, v253, 16
	s_add_i32 s18, s18, 1
	s_mov_b64 s[14:15], -1
	s_nop 2
	global_load_dword v2, v1, s[12:13] sc1
	s_waitcnt vmcnt(0)
	v_cmp_ge_u32_e32 vcc, v2, v0
	s_orn2_b64 s[12:13], vcc, exec
	s_branch .LBB0_1553

.LBB0_1567:
	s_or_b64 exec, exec, s[6:7]
	s_waitcnt vmcnt(0)
	v_readfirstlane_b32 s4, v3
	v_sub_u32_e32 v4, 0, v2
	s_mov_b64 s[6:7], 0
	v_add_u32_e32 v3, s4, v0
	v_cvt_f32_u32_e32 v0, v2
	v_readlane_b32 s4, v253, 17
	v_readlane_b32 s5, v253, 18
	v_rcp_iflag_f32_e32 v0, v0
	s_nop 0
	v_mul_f32_e32 v0, 0x4f7ffffe, v0
	v_cvt_u32_f32_e32 v0, v0
	v_mul_lo_u32 v4, v4, v0
	v_mul_hi_u32 v4, v0, v4
	v_add_u32_e32 v0, v0, v4
	v_mul_hi_u32 v0, v3, v0
	v_mul_lo_u32 v4, v0, v2
	v_sub_u32_e32 v4, v3, v4
	v_cmp_ge_u32_e32 vcc, v4, v2
	v_add_u32_e32 v5, 1, v0
	v_add_u32_e32 v3, 1, v3
	v_cndmask_b32_e32 v0, v0, v5, vcc
	v_sub_u32_e32 v5, v4, v2
	v_cndmask_b32_e32 v4, v4, v5, vcc
	v_cmp_ge_u32_e32 vcc, v4, v2
	v_add_u32_e32 v4, 1, v0
	s_nop 0
	v_cndmask_b32_e32 v0, v0, v4, vcc
	v_mul_lo_u32 v4, v2, v0
	v_add_u32_e32 v2, v4, v2
	v_cmp_ne_u32_e32 vcc, v3, v2
	v_mov_b32_e32 v0, v2
	v_mov_b64_e32 v[2:3], s[4:5]
	s_and_saveexec_b64 s[4:5], vcc
	s_cbranch_execz .LBB0_1579
	v_readlane_b32 s6, v253, 15
	v_readlane_b32 s7, v253, 16
	s_mov_b64 s[8:9], 0
	s_nop 3
	global_load_dword v2, v1, s[6:7] sc1
	s_waitcnt vmcnt(0)
	v_cmp_lt_u32_e32 vcc, v2, v0
	s_and_saveexec_b64 s[6:7], vcc
	s_cbranch_execz .LBB0_1578
	s_mov_b32 s18, 1
	s_branch .LBB0_1571

.LBB0_3216:
	v_readlane_b32 s4, v253, 11
	v_readlane_b32 s5, v253, 12
	v_cvt_f32_u32_e32 v0, v3
	v_sub_u32_e32 v5, 0, v3
	v_rcp_iflag_f32_e32 v0, v0
	s_nop 1
	global_atomic_add v4, v1, v252, s[4:5] sc0
	v_mul_f32_e32 v0, 0x4f7ffffe, v0
	v_cvt_u32_f32_e32 v0, v0
	v_mul_lo_u32 v5, v5, v0
	v_mul_hi_u32 v5, v0, v5
	v_add_u32_e32 v0, v0, v5
	s_waitcnt vmcnt(0)
	v_mul_hi_u32 v0, v4, v0
	v_mul_lo_u32 v5, v0, v3
	v_sub_u32_e32 v5, v4, v5
	v_add_u32_e32 v6, 1, v0
	v_cmp_ge_u32_e32 vcc, v5, v3
	v_add_u32_e32 v4, 1, v4
	s_nop 0
	v_cndmask_b32_e32 v0, v0, v6, vcc
	v_sub_u32_e32 v6, v5, v3
	v_cndmask_b32_e32 v5, v5, v6, vcc
	v_add_u32_e32 v6, 1, v0
	v_cmp_ge_u32_e32 vcc, v5, v3
	s_nop 1
	v_cndmask_b32_e32 v0, v0, v6, vcc
	v_mul_lo_u32 v5, v3, v0
	v_add_u32_e32 v3, v5, v3
	v_cmp_ne_u32_e32 vcc, v4, v3
	s_and_saveexec_b64 s[4:5], vcc
	s_xor_b64 s[4:5], exec, s[4:5]
	s_cbranch_execz .LBB0_3230
	v_readlane_b32 s6, v253, 15
	v_readlane_b32 s7, v253, 16
	s_waitcnt lgkmcnt(0)
	v_add_u32_e32 v0, 1, v0
	v_mul_lo_u32 v0, v0, v2
	s_nop 3
	global_load_dword v2, v1, s[6:7] sc1
	s_waitcnt vmcnt(0)
	v_cmp_lt_u32_e32 vcc, v2, v0
	s_and_saveexec_b64 s[6:7], vcc
	s_cbranch_execz .LBB0_3229
	s_mov_b32 s20, 1
	s_mov_b64 s[10:11], 0
	s_branch .LBB0_3220

.LBB0_3222:
	v_readlane_b32 s14, v253, 15
	v_readlane_b32 s15, v253, 16
	s_add_i32 s20, s20, 1
	s_mov_b64 s[16:17], -1
	s_nop 2
	global_load_dword v2, v1, s[14:15] sc1
	s_waitcnt vmcnt(0)
	v_cmp_ge_u32_e32 vcc, v2, v0
	s_orn2_b64 s[14:15], vcc, exec
	s_branch .LBB0_3219

.LBB0_3233:
	s_or_b64 exec, exec, s[6:7]
	s_waitcnt vmcnt(0)
	v_readfirstlane_b32 s4, v3
	v_sub_u32_e32 v4, 0, v2
	s_mov_b64 s[6:7], 0
	v_add_u32_e32 v3, s4, v0
	v_cvt_f32_u32_e32 v0, v2
	v_readlane_b32 s4, v253, 17
	v_readlane_b32 s5, v253, 18
	v_rcp_iflag_f32_e32 v0, v0
	s_nop 0
	v_mul_f32_e32 v0, 0x4f7ffffe, v0
	v_cvt_u32_f32_e32 v0, v0
	v_mul_lo_u32 v4, v4, v0
	v_mul_hi_u32 v4, v0, v4
	v_add_u32_e32 v0, v0, v4
	v_mul_hi_u32 v0, v3, v0
	v_mul_lo_u32 v4, v0, v2
	v_sub_u32_e32 v4, v3, v4
	v_cmp_ge_u32_e32 vcc, v4, v2
	v_add_u32_e32 v5, 1, v0
	v_add_u32_e32 v3, 1, v3
	v_cndmask_b32_e32 v0, v0, v5, vcc
	v_sub_u32_e32 v5, v4, v2
	v_cndmask_b32_e32 v4, v4, v5, vcc
	v_cmp_ge_u32_e32 vcc, v4, v2
	v_add_u32_e32 v4, 1, v0
	s_nop 0
	v_cndmask_b32_e32 v0, v0, v4, vcc
	v_mul_lo_u32 v4, v2, v0
	v_add_u32_e32 v2, v4, v2
	v_cmp_ne_u32_e32 vcc, v3, v2
	v_mov_b32_e32 v0, v2
	v_mov_b64_e32 v[2:3], s[4:5]
	s_and_saveexec_b64 s[4:5], vcc
	s_cbranch_execz .LBB0_3245
	v_readlane_b32 s6, v253, 15
	v_readlane_b32 s7, v253, 16
	s_mov_b64 s[10:11], 0
	s_nop 3
	global_load_dword v2, v1, s[6:7] sc1
	s_waitcnt vmcnt(0)
	v_cmp_lt_u32_e32 vcc, v2, v0
	s_and_saveexec_b64 s[6:7], vcc
	s_cbranch_execz .LBB0_3244
	s_mov_b32 s20, 1
	s_branch .LBB0_3237
